# MoBA near-tile path: T5-bias table reads issued up front into the dead next-score registers, bias adds folded into the PV MFMA gaps (no serial bias block between PV and QK)
# speedup vs baseline: 1.0001x; 1.0001x over previous
.Lmb1_skVAn:
.Lmb1_A_g0near:
	s_lshr_b32 s44, s34, 2
	s_cmp_eq_u32 s44, s91
	s_cselect_b64 s[8:9], -1, 0
	s_lshl_b32 s44, 1, s44
	v_and_b32_e32 v219, s44, v129
	v_cmp_ne_u32_e32 vcc, 0, v219
	s_or_b64 vcc, s[8:9], vcc
	s_nop 0
	v_cndmask_b32_e32 v219, v127, v112, vcc
	v_lshl_add_u32 v219, v219, 2, 0
	v_add_u32_e32 v219, 0x1d000, v219
	ds_read2_b32 v[236:237], v219 offset0:58 offset1:59
	ds_read2_b32 v[238:239], v219 offset0:56 offset1:57
	ds_read2_b32 v[240:241], v219 offset0:50 offset1:51
	ds_read2_b32 v[242:243], v219 offset0:48 offset1:49
	ds_read2_b32 v[244:245], v219 offset0:42 offset1:43
	ds_read2_b32 v[246:247], v219 offset0:40 offset1:41
	ds_read2_b32 v[248:249], v219 offset0:34 offset1:35
	ds_read2_b32 v[250:251], v219 offset0:32 offset1:33
	ds_read2_b32 v[134:135], v219 offset0:26 offset1:27
	ds_read2_b32 v[136:137], v219 offset0:24 offset1:25
	ds_read2_b32 v[138:139], v219 offset0:18 offset1:19
	ds_read2_b32 v[140:141], v219 offset0:16 offset1:17
	ds_read2_b32 v[142:143], v219 offset0:10 offset1:11
	ds_read2_b32 v[144:145], v219 offset0:8 offset1:9
	ds_read2_b32 v[146:147], v219 offset0:2 offset1:3
	ds_read2_b32 v[148:149], v219 offset1:1
	v_mfma_f32_32x32x16_bf16 v[16:31], v[108:111], v[186:189], v[16:31]
	v_mfma_f32_32x32x16_bf16 v[16:31], v[104:107], v[190:193], v[16:31]
	v_mfma_f32_32x32x16_bf16 v[16:31], v[100:103], v[194:197], v[16:31]
	v_mfma_f32_32x32x16_bf16 v[16:31], v[96:99], v[198:201], v[16:31]
	s_waitcnt lgkmcnt(0)
	v_mfma_f32_32x32x16_bf16 v[32:47], v[108:111], v[202:205], v[32:47]
	v_add_f32_e32 v64, v64, v237
	v_add_f32_e32 v65, v65, v236
	v_add_f32_e32 v66, v66, v239
	v_add_f32_e32 v67, v67, v238
	v_add_f32_e32 v68, v68, v241
	v_add_f32_e32 v69, v69, v240
	v_add_f32_e32 v70, v70, v243
	v_add_f32_e32 v71, v71, v242
	v_mfma_f32_32x32x16_bf16 v[32:47], v[104:107], v[206:209], v[32:47]
	v_add_f32_e32 v72, v72, v245
	v_add_f32_e32 v73, v73, v244
	v_add_f32_e32 v74, v74, v247
	v_add_f32_e32 v75, v75, v246
	v_add_f32_e32 v76, v76, v249
	v_add_f32_e32 v77, v77, v248
	v_add_f32_e32 v78, v78, v251
	v_add_f32_e32 v79, v79, v250
	v_mfma_f32_32x32x16_bf16 v[32:47], v[100:103], v[210:213], v[32:47]
	v_add_f32_e32 v48, v48, v135
	v_add_f32_e32 v49, v49, v134
	v_add_f32_e32 v50, v50, v137
	v_add_f32_e32 v51, v51, v136
	v_add_f32_e32 v52, v52, v139
	v_add_f32_e32 v53, v53, v138
	v_add_f32_e32 v54, v54, v141
	v_add_f32_e32 v55, v55, v140
	v_mfma_f32_32x32x16_bf16 v[32:47], v[96:99], v[214:217], v[32:47]
	v_add_f32_e32 v56, v56, v143
	v_add_f32_e32 v57, v57, v142
	v_add_f32_e32 v58, v58, v145
	v_add_f32_e32 v59, v59, v144
	v_add_f32_e32 v60, v60, v147
	v_add_f32_e32 v61, v61, v146
	v_add_f32_e32 v62, v62, v149
	v_add_f32_e32 v63, v63, v148
	s_waitcnt lgkmcnt(0)
	v_mfma_f32_32x32x16_bf16 v[236:251], v[154:157], v[92:95], v[220:235]
	ds_read_b64_tr_b16 v[186:187], v218
	ds_read_b64_tr_b16 v[188:189], v218 offset:512
	ds_read_b64_tr_b16 v[190:191], v218 offset:1024
	ds_read_b64_tr_b16 v[192:193], v218 offset:1536
	ds_read_b64_tr_b16 v[194:195], v218 offset:2048
	ds_read_b64_tr_b16 v[196:197], v218 offset:2560
	ds_read_b64_tr_b16 v[198:199], v218 offset:3072
	ds_read_b64_tr_b16 v[200:201], v218 offset:3584
	ds_read_b64_tr_b16 v[202:203], v218 offset:4096
	ds_read_b64_tr_b16 v[204:205], v218 offset:4608
	ds_read_b64_tr_b16 v[206:207], v218 offset:5120
	v_mfma_f32_32x32x16_bf16 v[134:149], v[158:161], v[92:95], v[220:235]
	ds_read_b64_tr_b16 v[208:209], v218 offset:5632
	ds_read_b64_tr_b16 v[210:211], v218 offset:6144
	ds_read_b64_tr_b16 v[212:213], v218 offset:6656
	ds_read_b64_tr_b16 v[214:215], v218 offset:7168
	ds_read_b64_tr_b16 v[216:217], v218 offset:7680
	v_exp_f32_e32 v64, v64
	v_exp_f32_e32 v48, v48
	v_exp_f32_e32 v65, v65
	v_exp_f32_e32 v49, v49
	v_exp_f32_e32 v66, v66
	v_exp_f32_e32 v50, v50
	v_mfma_f32_32x32x16_bf16 v[236:251], v[162:165], v[88:91], v[236:251]
	v_exp_f32_e32 v67, v67
	v_exp_f32_e32 v51, v51
	v_add_f32_e32 v252, v48, v64
	v_exp_f32_e32 v68, v68
	v_exp_f32_e32 v52, v52
	v_add_f32_e32 v252, 0, v252
	v_add_f32_e32 v253, v49, v65
	v_exp_f32_e32 v69, v69
	v_exp_f32_e32 v53, v53
	v_add_f32_e32 v252, v253, v252
	v_add_f32_e32 v253, v50, v66
	v_mfma_f32_32x32x16_bf16 v[134:149], v[166:169], v[88:91], v[134:149]
	v_exp_f32_e32 v70, v70
	v_exp_f32_e32 v54, v54
	v_add_f32_e32 v252, v253, v252
	v_add_f32_e32 v253, v51, v67
	v_exp_f32_e32 v71, v71
	v_exp_f32_e32 v55, v55
	v_add_f32_e32 v252, v253, v252
	v_add_f32_e32 v253, v52, v68
	v_exp_f32_e32 v72, v72
	v_exp_f32_e32 v56, v56
	v_add_f32_e32 v252, v253, v252
	v_mfma_f32_32x32x16_bf16 v[236:251], v[170:173], v[84:87], v[236:251]
	v_add_f32_e32 v253, v53, v69
	v_exp_f32_e32 v73, v73
	v_exp_f32_e32 v57, v57
	v_add_f32_e32 v252, v253, v252
	v_add_f32_e32 v253, v54, v70
	v_exp_f32_e32 v74, v74
	v_exp_f32_e32 v58, v58
	v_add_f32_e32 v252, v253, v252
	v_add_f32_e32 v253, v55, v71
	v_exp_f32_e32 v75, v75
	v_exp_f32_e32 v59, v59
	v_mfma_f32_32x32x16_bf16 v[134:149], v[174:177], v[84:87], v[134:149]
	v_add_f32_e32 v252, v253, v252
	v_add_f32_e32 v253, v56, v72
	v_exp_f32_e32 v76, v76
	v_exp_f32_e32 v60, v60
	v_add_f32_e32 v252, v253, v252
	v_add_f32_e32 v253, v57, v73
	v_exp_f32_e32 v77, v77
	v_exp_f32_e32 v61, v61
	v_add_f32_e32 v252, v253, v252
	v_add_f32_e32 v253, v58, v74
	v_exp_f32_e32 v78, v78
	v_mfma_f32_32x32x16_bf16 v[236:251], v[178:181], v[80:83], v[236:251]
	v_exp_f32_e32 v62, v62
	v_add_f32_e32 v252, v253, v252
	v_add_f32_e32 v253, v59, v75
	v_exp_f32_e32 v79, v79
	v_exp_f32_e32 v63, v63
	v_add_f32_e32 v252, v253, v252
	v_add_f32_e32 v253, v60, v76
	v_add_f32_e32 v252, v253, v252
	v_add_f32_e32 v253, v61, v77
	v_add_f32_e32 v252, v253, v252
	v_add_f32_e32 v253, v62, v78
	v_mfma_f32_32x32x16_bf16 v[134:149], v[182:185], v[80:83], v[134:149]
	v_add_f32_e32 v252, v253, v252
	v_add_f32_e32 v253, v63, v79
	v_add_f32_e32 v252, v253, v252
	v_add_f32_e32 v131, v131, v252
	v_cvt_pk_bf16_f32 v108, v64, v65
	v_cvt_pk_bf16_f32 v109, v66, v67
	v_cvt_pk_bf16_f32 v110, v68, v69
	v_cvt_pk_bf16_f32 v111, v70, v71
	v_cvt_pk_bf16_f32 v104, v72, v73
	v_cvt_pk_bf16_f32 v105, v74, v75
	v_cvt_pk_bf16_f32 v106, v76, v77
	v_cvt_pk_bf16_f32 v107, v78, v79
	v_cvt_pk_bf16_f32 v100, v48, v49
	v_cvt_pk_bf16_f32 v101, v50, v51
	v_cvt_pk_bf16_f32 v102, v52, v53
	v_cvt_pk_bf16_f32 v103, v54, v55
	v_cvt_pk_bf16_f32 v96, v56, v57
	v_cvt_pk_bf16_f32 v97, v58, v59
	v_cvt_pk_bf16_f32 v98, v60, v61
	v_cvt_pk_bf16_f32 v99, v62, v63
	s_branch .Lmb1_A_tail

; #define ATT_MFMA(a, b, c) __builtin_amdgcn_mfma_f32_32x32x16_bf16((a), (b), (c), 0, 0, 0)
; #define ATT_RDTR(dst, addr, off) asm volatile("ds_read_b64_tr_b16 %0, %1 offset:%c2" : "=&v"(dst) : "v"(addr), "i"(off) : "memory")
; template <bool DO_QK, bool DO_PV> __device__ __forceinline__ void mseg(f32x16& p0, f32x16& p1, f32x16* o, unsigned kaddr, unsigned vaddr, const bf16x8* qr, const f32x16& cin,
;                                                                      bf16x8 pa0, bf16x8 pa1, bf16x8 pa2, bf16x8 pa3) {
;     ...
;     if (DO_PV) {
;         if (!DO_QK) asm volatile("s_waitcnt lgkmcnt(0)" : "+v"(vl[0]), "+v"(vh[0]), "+v"(vl[1]), "+v"(vh[1]), "+v"(vl[2]), "+v"(vh[2]), "+v"(vl[3]), "+v"(vh[3]) :: "memory");
;         __builtin_amdgcn_sched_barrier(0);
;     ...
;         o[0] = ATT_MFMA(pa0, ATT_PK2(vl[0], vh[0]), o[0]); o[0] = ATT_MFMA(pa1, ATT_PK2(vl[1], vh[1]), o[0]);
;         o[0] = ATT_MFMA(pa2, ATT_PK2(vl[2], vh[2]), o[0]); o[0] = ATT_MFMA(pa3, ATT_PK2(vl[3], vh[3]), o[0]);
;         __builtin_amdgcn_sched_barrier(0);
;         ATT_RDTR(vl[0], vaddr, 4096); ATT_RDTR(vh[0], vaddr, 4608); ATT_RDTR(vl[1], vaddr, 5120); ATT_RDTR(vh[1], vaddr, 5632);
;         ATT_RDTR(vl[2], vaddr, 6144); ATT_RDTR(vh[2], vaddr, 6656); ATT_RDTR(vl[3], vaddr, 7168); ATT_RDTR(vh[3], vaddr, 7680);
;         asm volatile("s_waitcnt lgkmcnt(0)" : "+v"(vl[0]), "+v"(vh[0]), "+v"(vl[1]), "+v"(vh[1]), "+v"(vl[2]), "+v"(vh[2]), "+v"(vl[3]), "+v"(vh[3]) :: "memory");
;         __builtin_amdgcn_sched_barrier(0);
;         o[1] = ATT_MFMA(pa0, ATT_PK2(vl[0], vh[0]), o[1]); o[1] = ATT_MFMA(pa1, ATT_PK2(vl[1], vh[1]), o[1]);
;         o[1] = ATT_MFMA(pa2, ATT_PK2(vl[2], vh[2]), o[1]); o[1] = ATT_MFMA(pa3, ATT_PK2(vl[3], vh[3]), o[1]);
.Lmb1_skVBn:
.Lmb1_B_g0near:
	s_lshr_b32 s44, s34, 2
	s_cmp_eq_u32 s44, s91
	s_cselect_b64 s[8:9], -1, 0
	s_lshl_b32 s44, 1, s44
	v_and_b32_e32 v219, s44, v129
	v_cmp_ne_u32_e32 vcc, 0, v219
	s_or_b64 vcc, s[8:9], vcc
	s_nop 0
	v_cndmask_b32_e32 v219, v127, v112, vcc
	v_lshl_add_u32 v219, v219, 2, 0
	v_add_u32_e32 v219, 0x1d000, v219
	ds_read2_b32 v[64:65], v219 offset0:58 offset1:59
	ds_read2_b32 v[66:67], v219 offset0:56 offset1:57
	ds_read2_b32 v[68:69], v219 offset0:50 offset1:51
	ds_read2_b32 v[70:71], v219 offset0:48 offset1:49
	ds_read2_b32 v[72:73], v219 offset0:42 offset1:43
	ds_read2_b32 v[74:75], v219 offset0:40 offset1:41
	ds_read2_b32 v[76:77], v219 offset0:34 offset1:35
	ds_read2_b32 v[78:79], v219 offset0:32 offset1:33
	ds_read2_b32 v[48:49], v219 offset0:26 offset1:27
	ds_read2_b32 v[50:51], v219 offset0:24 offset1:25
	ds_read2_b32 v[52:53], v219 offset0:18 offset1:19
	ds_read2_b32 v[54:55], v219 offset0:16 offset1:17
	ds_read2_b32 v[56:57], v219 offset0:10 offset1:11
	ds_read2_b32 v[58:59], v219 offset0:8 offset1:9
	ds_read2_b32 v[60:61], v219 offset0:2 offset1:3
	ds_read2_b32 v[62:63], v219 offset1:1
	v_mfma_f32_32x32x16_bf16 v[16:31], v[108:111], v[186:189], v[16:31]
	v_mfma_f32_32x32x16_bf16 v[16:31], v[104:107], v[190:193], v[16:31]
	v_mfma_f32_32x32x16_bf16 v[16:31], v[100:103], v[194:197], v[16:31]
	v_mfma_f32_32x32x16_bf16 v[16:31], v[96:99], v[198:201], v[16:31]
	s_waitcnt lgkmcnt(0)
	v_mfma_f32_32x32x16_bf16 v[32:47], v[108:111], v[202:205], v[32:47]
	v_add_f32_e32 v236, v236, v65
	v_add_f32_e32 v237, v237, v64
	v_add_f32_e32 v238, v238, v67
	v_add_f32_e32 v239, v239, v66
	v_add_f32_e32 v240, v240, v69
	v_add_f32_e32 v241, v241, v68
	v_add_f32_e32 v242, v242, v71
	v_add_f32_e32 v243, v243, v70
	v_mfma_f32_32x32x16_bf16 v[32:47], v[104:107], v[206:209], v[32:47]
	v_add_f32_e32 v244, v244, v73
	v_add_f32_e32 v245, v245, v72
	v_add_f32_e32 v246, v246, v75
	v_add_f32_e32 v247, v247, v74
	v_add_f32_e32 v248, v248, v77
	v_add_f32_e32 v249, v249, v76
	v_add_f32_e32 v250, v250, v79
	v_add_f32_e32 v251, v251, v78
	v_mfma_f32_32x32x16_bf16 v[32:47], v[100:103], v[210:213], v[32:47]
	v_add_f32_e32 v134, v134, v49
	v_add_f32_e32 v135, v135, v48
	v_add_f32_e32 v136, v136, v51
	v_add_f32_e32 v137, v137, v50
	v_add_f32_e32 v138, v138, v53
	v_add_f32_e32 v139, v139, v52
	v_add_f32_e32 v140, v140, v55
	v_add_f32_e32 v141, v141, v54
	v_mfma_f32_32x32x16_bf16 v[32:47], v[96:99], v[214:217], v[32:47]
	v_add_f32_e32 v142, v142, v57
	v_add_f32_e32 v143, v143, v56
	v_add_f32_e32 v144, v144, v59
	v_add_f32_e32 v145, v145, v58
	v_add_f32_e32 v146, v146, v61
	v_add_f32_e32 v147, v147, v60
	v_add_f32_e32 v148, v148, v63
	v_add_f32_e32 v149, v149, v62
	s_waitcnt lgkmcnt(0)
	v_mfma_f32_32x32x16_bf16 v[64:79], v[154:157], v[92:95], v[220:235]
	ds_read_b64_tr_b16 v[186:187], v218
	ds_read_b64_tr_b16 v[188:189], v218 offset:512
	ds_read_b64_tr_b16 v[190:191], v218 offset:1024
	ds_read_b64_tr_b16 v[192:193], v218 offset:1536
	ds_read_b64_tr_b16 v[194:195], v218 offset:2048
	ds_read_b64_tr_b16 v[196:197], v218 offset:2560
	ds_read_b64_tr_b16 v[198:199], v218 offset:3072
	ds_read_b64_tr_b16 v[200:201], v218 offset:3584
	ds_read_b64_tr_b16 v[202:203], v218 offset:4096
	ds_read_b64_tr_b16 v[204:205], v218 offset:4608
	ds_read_b64_tr_b16 v[206:207], v218 offset:5120
	v_mfma_f32_32x32x16_bf16 v[48:63], v[158:161], v[92:95], v[220:235]
	ds_read_b64_tr_b16 v[208:209], v218 offset:5632
	ds_read_b64_tr_b16 v[210:211], v218 offset:6144
	ds_read_b64_tr_b16 v[212:213], v218 offset:6656
	ds_read_b64_tr_b16 v[214:215], v218 offset:7168
	ds_read_b64_tr_b16 v[216:217], v218 offset:7680
	v_exp_f32_e32 v236, v236
	v_exp_f32_e32 v134, v134
	v_exp_f32_e32 v237, v237
	v_exp_f32_e32 v135, v135
	v_exp_f32_e32 v238, v238
	v_exp_f32_e32 v136, v136
	v_mfma_f32_32x32x16_bf16 v[64:79], v[162:165], v[88:91], v[64:79]
	v_exp_f32_e32 v239, v239
	v_exp_f32_e32 v137, v137
	v_add_f32_e32 v252, v134, v236
	v_exp_f32_e32 v240, v240
	v_exp_f32_e32 v138, v138
	v_add_f32_e32 v252, 0, v252
	v_add_f32_e32 v253, v135, v237
	v_exp_f32_e32 v241, v241
	v_exp_f32_e32 v139, v139
	v_add_f32_e32 v252, v253, v252
	v_add_f32_e32 v253, v136, v238
	v_mfma_f32_32x32x16_bf16 v[48:63], v[166:169], v[88:91], v[48:63]
	v_exp_f32_e32 v242, v242
	v_exp_f32_e32 v140, v140
	v_add_f32_e32 v252, v253, v252
	v_add_f32_e32 v253, v137, v239
	v_exp_f32_e32 v243, v243
	v_exp_f32_e32 v141, v141
	v_add_f32_e32 v252, v253, v252
	v_add_f32_e32 v253, v138, v240
	v_exp_f32_e32 v244, v244
	v_exp_f32_e32 v142, v142
	v_add_f32_e32 v252, v253, v252
	v_mfma_f32_32x32x16_bf16 v[64:79], v[170:173], v[84:87], v[64:79]
	v_add_f32_e32 v253, v139, v241
	v_exp_f32_e32 v245, v245
	v_exp_f32_e32 v143, v143
	v_add_f32_e32 v252, v253, v252
	v_add_f32_e32 v253, v140, v242
	v_exp_f32_e32 v246, v246
	v_exp_f32_e32 v144, v144
	v_add_f32_e32 v252, v253, v252
	v_add_f32_e32 v253, v141, v243
	v_exp_f32_e32 v247, v247
	v_exp_f32_e32 v145, v145
	v_mfma_f32_32x32x16_bf16 v[48:63], v[174:177], v[84:87], v[48:63]
	v_add_f32_e32 v252, v253, v252
	v_add_f32_e32 v253, v142, v244
	v_exp_f32_e32 v248, v248
	v_exp_f32_e32 v146, v146
	v_add_f32_e32 v252, v253, v252
	v_add_f32_e32 v253, v143, v245
	v_exp_f32_e32 v249, v249
	v_exp_f32_e32 v147, v147
	v_add_f32_e32 v252, v253, v252
	v_add_f32_e32 v253, v144, v246
	v_exp_f32_e32 v250, v250
	v_mfma_f32_32x32x16_bf16 v[64:79], v[178:181], v[80:83], v[64:79]
	v_exp_f32_e32 v148, v148
	v_add_f32_e32 v252, v253, v252
	v_add_f32_e32 v253, v145, v247
	v_exp_f32_e32 v251, v251
	v_exp_f32_e32 v149, v149
	v_add_f32_e32 v252, v253, v252
	v_add_f32_e32 v253, v146, v248
	v_add_f32_e32 v252, v253, v252
	v_add_f32_e32 v253, v147, v249
	v_add_f32_e32 v252, v253, v252
	v_add_f32_e32 v253, v148, v250
	v_mfma_f32_32x32x16_bf16 v[48:63], v[182:185], v[80:83], v[48:63]
	v_add_f32_e32 v252, v253, v252
	v_add_f32_e32 v253, v149, v251
	v_add_f32_e32 v252, v253, v252
	v_add_f32_e32 v131, v131, v252
	v_cvt_pk_bf16_f32 v108, v236, v237
	v_cvt_pk_bf16_f32 v109, v238, v239
	v_cvt_pk_bf16_f32 v110, v240, v241
	v_cvt_pk_bf16_f32 v111, v242, v243
	v_cvt_pk_bf16_f32 v104, v244, v245
	v_cvt_pk_bf16_f32 v105, v246, v247
	v_cvt_pk_bf16_f32 v106, v248, v249
	v_cvt_pk_bf16_f32 v107, v250, v251
	v_cvt_pk_bf16_f32 v100, v134, v135
	v_cvt_pk_bf16_f32 v101, v136, v137
	v_cvt_pk_bf16_f32 v102, v138, v139
	v_cvt_pk_bf16_f32 v103, v140, v141
	v_cvt_pk_bf16_f32 v96, v142, v143
	v_cvt_pk_bf16_f32 v97, v144, v145
	v_cvt_pk_bf16_f32 v98, v146, v147
	v_cvt_pk_bf16_f32 v99, v148, v149
	s_branch .Lmb1_B_tail

; #define ATT_MFMA(a, b, c) __builtin_amdgcn_mfma_f32_32x32x16_bf16((a), (b), (c), 0, 0, 0)
; #define ATT_RDTR(dst, addr, off) asm volatile("ds_read_b64_tr_b16 %0, %1 offset:%c2" : "=&v"(dst) : "v"(addr), "i"(off) : "memory")
; template <bool DO_QK, bool DO_PV> __device__ __forceinline__ void mseg(f32x16& p0, f32x16& p1, f32x16* o, unsigned kaddr, unsigned vaddr, const bf16x8* qr, const f32x16& cin,
;                                                                      bf16x8 pa0, bf16x8 pa1, bf16x8 pa2, bf16x8 pa3) {
;     ...
;     if (DO_PV) {
;         if (!DO_QK) asm volatile("s_waitcnt lgkmcnt(0)" : "+v"(vl[0]), "+v"(vh[0]), "+v"(vl[1]), "+v"(vh[1]), "+v"(vl[2]), "+v"(vh[2]), "+v"(vl[3]), "+v"(vh[3]) :: "memory");
;         __builtin_amdgcn_sched_barrier(0);
;     ...
;         o[0] = ATT_MFMA(pa0, ATT_PK2(vl[0], vh[0]), o[0]); o[0] = ATT_MFMA(pa1, ATT_PK2(vl[1], vh[1]), o[0]);
;         o[0] = ATT_MFMA(pa2, ATT_PK2(vl[2], vh[2]), o[0]); o[0] = ATT_MFMA(pa3, ATT_PK2(vl[3], vh[3]), o[0]);
;         __builtin_amdgcn_sched_barrier(0);
;         ATT_RDTR(vl[0], vaddr, 4096); ATT_RDTR(vh[0], vaddr, 4608); ATT_RDTR(vl[1], vaddr, 5120); ATT_RDTR(vh[1], vaddr, 5632);
;         ATT_RDTR(vl[2], vaddr, 6144); ATT_RDTR(vh[2], vaddr, 6656); ATT_RDTR(vl[3], vaddr, 7168); ATT_RDTR(vh[3], vaddr, 7680);
;         asm volatile("s_waitcnt lgkmcnt(0)" : "+v"(vl[0]), "+v"(vh[0]), "+v"(vl[1]), "+v"(vh[1]), "+v"(vl[2]), "+v"(vh[2]), "+v"(vl[3]), "+v"(vh[3]) :: "memory");
;         __builtin_amdgcn_sched_barrier(0);
;         o[1] = ATT_MFMA(pa0, ATT_PK2(vl[0], vh[0]), o[1]); o[1] = ATT_MFMA(pa1, ATT_PK2(vl[1], vh[1]), o[1]);
;         o[1] = ATT_MFMA(pa2, ATT_PK2(vl[2], vh[2]), o[1]); o[1] = ATT_MFMA(pa3, ATT_PK2(vl[3], vh[3]), o[1]);
.Lmb3_skVAn:
.Lmb3_A_g0near:
	s_lshr_b32 s42, s30, 2
	s_cmp_eq_u32 s42, s93
	s_cselect_b64 s[10:11], -1, 0
	s_lshl_b32 s42, 1, s42
	v_and_b32_e32 v219, s42, v129
	v_cmp_ne_u32_e32 vcc, 0, v219
	s_or_b64 vcc, s[10:11], vcc
	s_nop 0
	v_cndmask_b32_e32 v219, v127, v112, vcc
	v_lshl_add_u32 v219, v219, 2, 0
	v_add_u32_e32 v219, 0x1d000, v219
	ds_read2_b32 v[236:237], v219 offset0:58 offset1:59
	ds_read2_b32 v[238:239], v219 offset0:56 offset1:57
	ds_read2_b32 v[240:241], v219 offset0:50 offset1:51
	ds_read2_b32 v[242:243], v219 offset0:48 offset1:49
	ds_read2_b32 v[244:245], v219 offset0:42 offset1:43
	ds_read2_b32 v[246:247], v219 offset0:40 offset1:41
	ds_read2_b32 v[248:249], v219 offset0:34 offset1:35
	ds_read2_b32 v[250:251], v219 offset0:32 offset1:33
	ds_read2_b32 v[134:135], v219 offset0:26 offset1:27
	ds_read2_b32 v[136:137], v219 offset0:24 offset1:25
	ds_read2_b32 v[138:139], v219 offset0:18 offset1:19
	ds_read2_b32 v[140:141], v219 offset0:16 offset1:17
	ds_read2_b32 v[142:143], v219 offset0:10 offset1:11
	ds_read2_b32 v[144:145], v219 offset0:8 offset1:9
	ds_read2_b32 v[146:147], v219 offset0:2 offset1:3
	ds_read2_b32 v[148:149], v219 offset1:1
	v_mfma_f32_32x32x16_bf16 v[16:31], v[108:111], v[186:189], v[16:31]
	v_mfma_f32_32x32x16_bf16 v[16:31], v[104:107], v[190:193], v[16:31]
	v_mfma_f32_32x32x16_bf16 v[16:31], v[100:103], v[194:197], v[16:31]
	v_mfma_f32_32x32x16_bf16 v[16:31], v[96:99], v[198:201], v[16:31]
	s_waitcnt lgkmcnt(0)
	v_mfma_f32_32x32x16_bf16 v[32:47], v[108:111], v[202:205], v[32:47]
	v_add_f32_e32 v64, v64, v237
	v_add_f32_e32 v65, v65, v236
	v_add_f32_e32 v66, v66, v239
	v_add_f32_e32 v67, v67, v238
	v_add_f32_e32 v68, v68, v241
	v_add_f32_e32 v69, v69, v240
	v_add_f32_e32 v70, v70, v243
	v_add_f32_e32 v71, v71, v242
	v_mfma_f32_32x32x16_bf16 v[32:47], v[104:107], v[206:209], v[32:47]
	v_add_f32_e32 v72, v72, v245
	v_add_f32_e32 v73, v73, v244
	v_add_f32_e32 v74, v74, v247
	v_add_f32_e32 v75, v75, v246
	v_add_f32_e32 v76, v76, v249
	v_add_f32_e32 v77, v77, v248
	v_add_f32_e32 v78, v78, v251
	v_add_f32_e32 v79, v79, v250
	v_mfma_f32_32x32x16_bf16 v[32:47], v[100:103], v[210:213], v[32:47]
	v_add_f32_e32 v48, v48, v135
	v_add_f32_e32 v49, v49, v134
	v_add_f32_e32 v50, v50, v137
	v_add_f32_e32 v51, v51, v136
	v_add_f32_e32 v52, v52, v139
	v_add_f32_e32 v53, v53, v138
	v_add_f32_e32 v54, v54, v141
	v_add_f32_e32 v55, v55, v140
	v_mfma_f32_32x32x16_bf16 v[32:47], v[96:99], v[214:217], v[32:47]
	v_add_f32_e32 v56, v56, v143
	v_add_f32_e32 v57, v57, v142
	v_add_f32_e32 v58, v58, v145
	v_add_f32_e32 v59, v59, v144
	v_add_f32_e32 v60, v60, v147
	v_add_f32_e32 v61, v61, v146
	v_add_f32_e32 v62, v62, v149
	v_add_f32_e32 v63, v63, v148
	s_waitcnt lgkmcnt(0)
	v_mfma_f32_32x32x16_bf16 v[236:251], v[154:157], v[92:95], v[220:235]
	ds_read_b64_tr_b16 v[186:187], v218
	ds_read_b64_tr_b16 v[188:189], v218 offset:512
	ds_read_b64_tr_b16 v[190:191], v218 offset:1024
	ds_read_b64_tr_b16 v[192:193], v218 offset:1536
	ds_read_b64_tr_b16 v[194:195], v218 offset:2048
	ds_read_b64_tr_b16 v[196:197], v218 offset:2560
	ds_read_b64_tr_b16 v[198:199], v218 offset:3072
	ds_read_b64_tr_b16 v[200:201], v218 offset:3584
	ds_read_b64_tr_b16 v[202:203], v218 offset:4096
	ds_read_b64_tr_b16 v[204:205], v218 offset:4608
	ds_read_b64_tr_b16 v[206:207], v218 offset:5120
	v_mfma_f32_32x32x16_bf16 v[134:149], v[158:161], v[92:95], v[220:235]
	ds_read_b64_tr_b16 v[208:209], v218 offset:5632
	ds_read_b64_tr_b16 v[210:211], v218 offset:6144
	ds_read_b64_tr_b16 v[212:213], v218 offset:6656
	ds_read_b64_tr_b16 v[214:215], v218 offset:7168
	ds_read_b64_tr_b16 v[216:217], v218 offset:7680
	v_exp_f32_e32 v64, v64
	v_exp_f32_e32 v48, v48
	v_exp_f32_e32 v65, v65
	v_exp_f32_e32 v49, v49
	v_exp_f32_e32 v66, v66
	v_exp_f32_e32 v50, v50
	v_mfma_f32_32x32x16_bf16 v[236:251], v[162:165], v[88:91], v[236:251]
	v_exp_f32_e32 v67, v67
	v_exp_f32_e32 v51, v51
	v_add_f32_e32 v252, v48, v64
	v_exp_f32_e32 v68, v68
	v_exp_f32_e32 v52, v52
	v_add_f32_e32 v252, 0, v252
	v_add_f32_e32 v253, v49, v65
	v_exp_f32_e32 v69, v69
	v_exp_f32_e32 v53, v53
	v_add_f32_e32 v252, v253, v252
	v_add_f32_e32 v253, v50, v66
	v_mfma_f32_32x32x16_bf16 v[134:149], v[166:169], v[88:91], v[134:149]
	v_exp_f32_e32 v70, v70
	v_exp_f32_e32 v54, v54
	v_add_f32_e32 v252, v253, v252
	v_add_f32_e32 v253, v51, v67
	v_exp_f32_e32 v71, v71
	v_exp_f32_e32 v55, v55
	v_add_f32_e32 v252, v253, v252
	v_add_f32_e32 v253, v52, v68
	v_exp_f32_e32 v72, v72
	v_exp_f32_e32 v56, v56
	v_add_f32_e32 v252, v253, v252
	v_mfma_f32_32x32x16_bf16 v[236:251], v[170:173], v[84:87], v[236:251]
	v_add_f32_e32 v253, v53, v69
	v_exp_f32_e32 v73, v73
	v_exp_f32_e32 v57, v57
	v_add_f32_e32 v252, v253, v252
	v_add_f32_e32 v253, v54, v70
	v_exp_f32_e32 v74, v74
	v_exp_f32_e32 v58, v58
	v_add_f32_e32 v252, v253, v252
	v_add_f32_e32 v253, v55, v71
	v_exp_f32_e32 v75, v75
	v_exp_f32_e32 v59, v59
	v_mfma_f32_32x32x16_bf16 v[134:149], v[174:177], v[84:87], v[134:149]
	v_add_f32_e32 v252, v253, v252
	v_add_f32_e32 v253, v56, v72
	v_exp_f32_e32 v76, v76
	v_exp_f32_e32 v60, v60
	v_add_f32_e32 v252, v253, v252
	v_add_f32_e32 v253, v57, v73
	v_exp_f32_e32 v77, v77
	v_exp_f32_e32 v61, v61
	v_add_f32_e32 v252, v253, v252
	v_add_f32_e32 v253, v58, v74
	v_exp_f32_e32 v78, v78
	v_mfma_f32_32x32x16_bf16 v[236:251], v[178:181], v[80:83], v[236:251]
	v_exp_f32_e32 v62, v62
	v_add_f32_e32 v252, v253, v252
	v_add_f32_e32 v253, v59, v75
	v_exp_f32_e32 v79, v79
	v_exp_f32_e32 v63, v63
	v_add_f32_e32 v252, v253, v252
	v_add_f32_e32 v253, v60, v76
	v_add_f32_e32 v252, v253, v252
	v_add_f32_e32 v253, v61, v77
	v_add_f32_e32 v252, v253, v252
	v_add_f32_e32 v253, v62, v78
	v_mfma_f32_32x32x16_bf16 v[134:149], v[182:185], v[80:83], v[134:149]
	v_add_f32_e32 v252, v253, v252
	v_add_f32_e32 v253, v63, v79
	v_add_f32_e32 v252, v253, v252
	v_add_f32_e32 v131, v131, v252
	v_cvt_pk_bf16_f32 v108, v64, v65
	v_cvt_pk_bf16_f32 v109, v66, v67
	v_cvt_pk_bf16_f32 v110, v68, v69
	v_cvt_pk_bf16_f32 v111, v70, v71
	v_cvt_pk_bf16_f32 v104, v72, v73
	v_cvt_pk_bf16_f32 v105, v74, v75
	v_cvt_pk_bf16_f32 v106, v76, v77
	v_cvt_pk_bf16_f32 v107, v78, v79
	v_cvt_pk_bf16_f32 v100, v48, v49
	v_cvt_pk_bf16_f32 v101, v50, v51
	v_cvt_pk_bf16_f32 v102, v52, v53
	v_cvt_pk_bf16_f32 v103, v54, v55
	v_cvt_pk_bf16_f32 v96, v56, v57
	v_cvt_pk_bf16_f32 v97, v58, v59
	v_cvt_pk_bf16_f32 v98, v60, v61
	v_cvt_pk_bf16_f32 v99, v62, v63
	s_branch .Lmb3_A_tail

; #define ATT_MFMA(a, b, c) __builtin_amdgcn_mfma_f32_32x32x16_bf16((a), (b), (c), 0, 0, 0)
; #define ATT_RDTR(dst, addr, off) asm volatile("ds_read_b64_tr_b16 %0, %1 offset:%c2" : "=&v"(dst) : "v"(addr), "i"(off) : "memory")
; template <bool DO_QK, bool DO_PV> __device__ __forceinline__ void mseg(f32x16& p0, f32x16& p1, f32x16* o, unsigned kaddr, unsigned vaddr, const bf16x8* qr, const f32x16& cin,
;                                                                      bf16x8 pa0, bf16x8 pa1, bf16x8 pa2, bf16x8 pa3) {
;     ...
;     if (DO_PV) {
;         if (!DO_QK) asm volatile("s_waitcnt lgkmcnt(0)" : "+v"(vl[0]), "+v"(vh[0]), "+v"(vl[1]), "+v"(vh[1]), "+v"(vl[2]), "+v"(vh[2]), "+v"(vl[3]), "+v"(vh[3]) :: "memory");
;         __builtin_amdgcn_sched_barrier(0);
;     ...
;         o[0] = ATT_MFMA(pa0, ATT_PK2(vl[0], vh[0]), o[0]); o[0] = ATT_MFMA(pa1, ATT_PK2(vl[1], vh[1]), o[0]);
;         o[0] = ATT_MFMA(pa2, ATT_PK2(vl[2], vh[2]), o[0]); o[0] = ATT_MFMA(pa3, ATT_PK2(vl[3], vh[3]), o[0]);
;         __builtin_amdgcn_sched_barrier(0);
;         ATT_RDTR(vl[0], vaddr, 4096); ATT_RDTR(vh[0], vaddr, 4608); ATT_RDTR(vl[1], vaddr, 5120); ATT_RDTR(vh[1], vaddr, 5632);
;         ATT_RDTR(vl[2], vaddr, 6144); ATT_RDTR(vh[2], vaddr, 6656); ATT_RDTR(vl[3], vaddr, 7168); ATT_RDTR(vh[3], vaddr, 7680);
;         asm volatile("s_waitcnt lgkmcnt(0)" : "+v"(vl[0]), "+v"(vh[0]), "+v"(vl[1]), "+v"(vh[1]), "+v"(vl[2]), "+v"(vh[2]), "+v"(vl[3]), "+v"(vh[3]) :: "memory");
;         __builtin_amdgcn_sched_barrier(0);
;         o[1] = ATT_MFMA(pa0, ATT_PK2(vl[0], vh[0]), o[1]); o[1] = ATT_MFMA(pa1, ATT_PK2(vl[1], vh[1]), o[1]);
;         o[1] = ATT_MFMA(pa2, ATT_PK2(vl[2], vh[2]), o[1]); o[1] = ATT_MFMA(pa3, ATT_PK2(vl[3], vh[3]), o[1]);
.Lmb3_skVBn:
.Lmb3_B_g0near:
	s_lshr_b32 s42, s30, 2
	s_cmp_eq_u32 s42, s93
	s_cselect_b64 s[10:11], -1, 0
	s_lshl_b32 s42, 1, s42
	v_and_b32_e32 v219, s42, v129
	v_cmp_ne_u32_e32 vcc, 0, v219
	s_or_b64 vcc, s[10:11], vcc
	s_nop 0
	v_cndmask_b32_e32 v219, v127, v112, vcc
	v_lshl_add_u32 v219, v219, 2, 0
	v_add_u32_e32 v219, 0x1d000, v219
	ds_read2_b32 v[64:65], v219 offset0:58 offset1:59
	ds_read2_b32 v[66:67], v219 offset0:56 offset1:57
	ds_read2_b32 v[68:69], v219 offset0:50 offset1:51
	ds_read2_b32 v[70:71], v219 offset0:48 offset1:49
	ds_read2_b32 v[72:73], v219 offset0:42 offset1:43
	ds_read2_b32 v[74:75], v219 offset0:40 offset1:41
	ds_read2_b32 v[76:77], v219 offset0:34 offset1:35
	ds_read2_b32 v[78:79], v219 offset0:32 offset1:33
	ds_read2_b32 v[48:49], v219 offset0:26 offset1:27
	ds_read2_b32 v[50:51], v219 offset0:24 offset1:25
	ds_read2_b32 v[52:53], v219 offset0:18 offset1:19
	ds_read2_b32 v[54:55], v219 offset0:16 offset1:17
	ds_read2_b32 v[56:57], v219 offset0:10 offset1:11
	ds_read2_b32 v[58:59], v219 offset0:8 offset1:9
	ds_read2_b32 v[60:61], v219 offset0:2 offset1:3
	ds_read2_b32 v[62:63], v219 offset1:1
	v_mfma_f32_32x32x16_bf16 v[16:31], v[108:111], v[186:189], v[16:31]
	v_mfma_f32_32x32x16_bf16 v[16:31], v[104:107], v[190:193], v[16:31]
	v_mfma_f32_32x32x16_bf16 v[16:31], v[100:103], v[194:197], v[16:31]
	v_mfma_f32_32x32x16_bf16 v[16:31], v[96:99], v[198:201], v[16:31]
	s_waitcnt lgkmcnt(0)
	v_mfma_f32_32x32x16_bf16 v[32:47], v[108:111], v[202:205], v[32:47]
	v_add_f32_e32 v236, v236, v65
	v_add_f32_e32 v237, v237, v64
	v_add_f32_e32 v238, v238, v67
	v_add_f32_e32 v239, v239, v66
	v_add_f32_e32 v240, v240, v69
	v_add_f32_e32 v241, v241, v68
	v_add_f32_e32 v242, v242, v71
	v_add_f32_e32 v243, v243, v70
	v_mfma_f32_32x32x16_bf16 v[32:47], v[104:107], v[206:209], v[32:47]
	v_add_f32_e32 v244, v244, v73
	v_add_f32_e32 v245, v245, v72
	v_add_f32_e32 v246, v246, v75
	v_add_f32_e32 v247, v247, v74
	v_add_f32_e32 v248, v248, v77
	v_add_f32_e32 v249, v249, v76
	v_add_f32_e32 v250, v250, v79
	v_add_f32_e32 v251, v251, v78
	v_mfma_f32_32x32x16_bf16 v[32:47], v[100:103], v[210:213], v[32:47]
	v_add_f32_e32 v134, v134, v49
	v_add_f32_e32 v135, v135, v48
	v_add_f32_e32 v136, v136, v51
	v_add_f32_e32 v137, v137, v50
	v_add_f32_e32 v138, v138, v53
	v_add_f32_e32 v139, v139, v52
	v_add_f32_e32 v140, v140, v55
	v_add_f32_e32 v141, v141, v54
	v_mfma_f32_32x32x16_bf16 v[32:47], v[96:99], v[214:217], v[32:47]
	v_add_f32_e32 v142, v142, v57
	v_add_f32_e32 v143, v143, v56
	v_add_f32_e32 v144, v144, v59
	v_add_f32_e32 v145, v145, v58
	v_add_f32_e32 v146, v146, v61
	v_add_f32_e32 v147, v147, v60
	v_add_f32_e32 v148, v148, v63
	v_add_f32_e32 v149, v149, v62
	s_waitcnt lgkmcnt(0)
	v_mfma_f32_32x32x16_bf16 v[64:79], v[154:157], v[92:95], v[220:235]
	ds_read_b64_tr_b16 v[186:187], v218
	ds_read_b64_tr_b16 v[188:189], v218 offset:512
	ds_read_b64_tr_b16 v[190:191], v218 offset:1024
	ds_read_b64_tr_b16 v[192:193], v218 offset:1536
	ds_read_b64_tr_b16 v[194:195], v218 offset:2048
	ds_read_b64_tr_b16 v[196:197], v218 offset:2560
	ds_read_b64_tr_b16 v[198:199], v218 offset:3072
	ds_read_b64_tr_b16 v[200:201], v218 offset:3584
	ds_read_b64_tr_b16 v[202:203], v218 offset:4096
	ds_read_b64_tr_b16 v[204:205], v218 offset:4608
	ds_read_b64_tr_b16 v[206:207], v218 offset:5120
	v_mfma_f32_32x32x16_bf16 v[48:63], v[158:161], v[92:95], v[220:235]
	ds_read_b64_tr_b16 v[208:209], v218 offset:5632
	ds_read_b64_tr_b16 v[210:211], v218 offset:6144
	ds_read_b64_tr_b16 v[212:213], v218 offset:6656
	ds_read_b64_tr_b16 v[214:215], v218 offset:7168
	ds_read_b64_tr_b16 v[216:217], v218 offset:7680
	v_exp_f32_e32 v236, v236
	v_exp_f32_e32 v134, v134
	v_exp_f32_e32 v237, v237
	v_exp_f32_e32 v135, v135
	v_exp_f32_e32 v238, v238
	v_exp_f32_e32 v136, v136
	v_mfma_f32_32x32x16_bf16 v[64:79], v[162:165], v[88:91], v[64:79]
	v_exp_f32_e32 v239, v239
	v_exp_f32_e32 v137, v137
	v_add_f32_e32 v252, v134, v236
	v_exp_f32_e32 v240, v240
	v_exp_f32_e32 v138, v138
	v_add_f32_e32 v252, 0, v252
	v_add_f32_e32 v253, v135, v237
	v_exp_f32_e32 v241, v241
	v_exp_f32_e32 v139, v139
	v_add_f32_e32 v252, v253, v252
	v_add_f32_e32 v253, v136, v238
	v_mfma_f32_32x32x16_bf16 v[48:63], v[166:169], v[88:91], v[48:63]
	v_exp_f32_e32 v242, v242
	v_exp_f32_e32 v140, v140
	v_add_f32_e32 v252, v253, v252
	v_add_f32_e32 v253, v137, v239
	v_exp_f32_e32 v243, v243
	v_exp_f32_e32 v141, v141
	v_add_f32_e32 v252, v253, v252
	v_add_f32_e32 v253, v138, v240
	v_exp_f32_e32 v244, v244
	v_exp_f32_e32 v142, v142
	v_add_f32_e32 v252, v253, v252
	v_mfma_f32_32x32x16_bf16 v[64:79], v[170:173], v[84:87], v[64:79]
	v_add_f32_e32 v253, v139, v241
	v_exp_f32_e32 v245, v245
	v_exp_f32_e32 v143, v143
	v_add_f32_e32 v252, v253, v252
	v_add_f32_e32 v253, v140, v242
	v_exp_f32_e32 v246, v246
	v_exp_f32_e32 v144, v144
	v_add_f32_e32 v252, v253, v252
	v_add_f32_e32 v253, v141, v243
	v_exp_f32_e32 v247, v247
	v_exp_f32_e32 v145, v145
	v_mfma_f32_32x32x16_bf16 v[48:63], v[174:177], v[84:87], v[48:63]
	v_add_f32_e32 v252, v253, v252
	v_add_f32_e32 v253, v142, v244
	v_exp_f32_e32 v248, v248
	v_exp_f32_e32 v146, v146
	v_add_f32_e32 v252, v253, v252
	v_add_f32_e32 v253, v143, v245
	v_exp_f32_e32 v249, v249
	v_exp_f32_e32 v147, v147
	v_add_f32_e32 v252, v253, v252
	v_add_f32_e32 v253, v144, v246
	v_exp_f32_e32 v250, v250
	v_mfma_f32_32x32x16_bf16 v[64:79], v[178:181], v[80:83], v[64:79]
	v_exp_f32_e32 v148, v148
	v_add_f32_e32 v252, v253, v252
	v_add_f32_e32 v253, v145, v247
	v_exp_f32_e32 v251, v251
	v_exp_f32_e32 v149, v149
	v_add_f32_e32 v252, v253, v252
	v_add_f32_e32 v253, v146, v248
	v_add_f32_e32 v252, v253, v252
	v_add_f32_e32 v253, v147, v249
	v_add_f32_e32 v252, v253, v252
	v_add_f32_e32 v253, v148, v250
	v_mfma_f32_32x32x16_bf16 v[48:63], v[182:185], v[80:83], v[48:63]
	v_add_f32_e32 v252, v253, v252
	v_add_f32_e32 v253, v149, v251
	v_add_f32_e32 v252, v253, v252
	v_add_f32_e32 v131, v131, v252
	v_cvt_pk_bf16_f32 v108, v236, v237
	v_cvt_pk_bf16_f32 v109, v238, v239
	v_cvt_pk_bf16_f32 v110, v240, v241
	v_cvt_pk_bf16_f32 v111, v242, v243
	v_cvt_pk_bf16_f32 v104, v244, v245
	v_cvt_pk_bf16_f32 v105, v246, v247
	v_cvt_pk_bf16_f32 v106, v248, v249
	v_cvt_pk_bf16_f32 v107, v250, v251
	v_cvt_pk_bf16_f32 v100, v134, v135
	v_cvt_pk_bf16_f32 v101, v136, v137
	v_cvt_pk_bf16_f32 v102, v138, v139
	v_cvt_pk_bf16_f32 v103, v140, v141
	v_cvt_pk_bf16_f32 v96, v142, v143
	v_cvt_pk_bf16_f32 v97, v144, v145
	v_cvt_pk_bf16_f32 v98, v146, v147
	v_cvt_pk_bf16_f32 v99, v148, v149
	s_branch .Lmb3_B_tail
